# GLA stage A1 pipelined over the 4 tiles in pass A and pass C, alr prefetch, P4 epilogue loads batched, first XCD arriver starts the L2 writeback at the P2a barrier
# speedup vs baseline: 1.0079x; 1.0016x over previous
; #define LAS __attribute__((address_space(3)))
; __device__ __forceinline__ void unpack8(const u32x4 w, float (&f)[8]) { f[0] = bflo(w.x); f[1] = bfhi(w.x); f[2] = bflo(w.y); f[3] = bfhi(w.y); f[4] = bflo(w.z); f[5] = bfhi(w.z); f[6] = bflo(w.w); f[7] = bfhi(w.w); }
; #define MFMA16(a, b, c) __builtin_amdgcn_mfma_f32_16x16x32_bf16((a), (b), (c), 0, 0, 0)
; __device__ __forceinline__ u32x4 pack8v(const float (&f)[8]) { u32x4 w; w.x = pk2v(f[0], f[1]); w.y = pk2v(f[2], f[3]); w.z = pk2v(f[4], f[5]); w.w = pk2v(f[6], f[7]); return w; }
; #define GLA_LOAD_QKV(T0) do { _Pragma("unroll") for (int i_ = 0; i_ < 2; ++i_) { const int oc_ = lo + 8 * i_; \
;             kw[i_] = *(const u32x4*)(QK + ((T0) + lt) * 1024 + 512 + h * 128 + oc_ * 8); } \
;         _Pragma("unroll") for (int i_ = 0; i_ < 4; ++i_) { const int oc_ = lo + 8 * i_; vw[i_] = *(const u32x4*)(GV + ((T0) + lt) * 1024 + h * 256 + oc_ * 8); } } while (0)
; template <bool FULL> ...
;     ...
;     for (int c = 0; c < GLA_SEGC; ++c) {
;         const size_t tok0 = tokb + (size_t)c * 64;
;         GLA_LOAD_QKV(tok0);
;         if (FULL) {
; #pragma unroll
;             for (int i = 0; i < 2; ++i) qw[i] = *(const u32x4*)(QK + (tok0 + lt) * 1024 + h * 128 + (lo + 8 * i) * 8); }
;         {
;             float carry = 0.f;
; #pragma unroll
;             for (int tt = 0; tt < 4; ++tt) {
;                 const LAS f32x4* ar = (const LAS f32x4*)(ALRS + (tt * 16 + fr) * 16 + (fq & 1) * 8); const f32x4 x0 = ar[0], x1 = ar[1];
;                 float x[8] = {x0.x, x0.y, x0.z, x0.w, x1.x, x1.y, x1.z, x1.w}, xh[8];
;                 unpack8(pack8v(x), xh);
;                 if (fq >= 2) {
; #pragma unroll
;                     for (int e = 0; e < 8; ++e) x[e] -= xh[e];
;                 }
;                 const bf16x8 af = __builtin_bit_cast(bf16x8, pack8v(x));
;                 const f32x4 z4 = MFMA16(af, w2f, ((f32x4){0.f, 0.f, 0.f, 0.f}));
;                 float v[4];
; #pragma unroll
;                 for (int i = 0; i < 4; ++i) { const float z = z4[i] + bz;
;                     v[i] = (fminf(z, 0.f) - 0.6931471805599453f * __builtin_amdgcn_logf(1.0f + __builtin_amdgcn_exp2f(-1.4426950408889634f * fabsf(z)))) * (1.0f / 16.0f); }
.LBB0_301:
	s_cmp_lg_u32 s24, 0xe0000
	s_cselect_b64 s[6:7], -1, 0
	s_and_b64 s[72:73], vcc, s[6:7]
	s_and_saveexec_b64 s[6:7], s[72:73]
	s_cbranch_execz .Lgla_a_noalr
	global_load_dwordx4 v[200:203], v[104:105], off
.Lgla_a_noalr:
	s_or_b64 exec, exec, s[6:7]
	v_lshl_add_u64 v[68:69], v[106:107], 0, s[24:25]
	v_add_co_u32_e64 v68, s[6:7], s28, v68
	s_nop 1
	v_addc_co_u32_e64 v69, s[6:7], 0, v69, s[6:7]
	global_load_dwordx4 v[88:91], v[68:69], off offset:1024
	global_load_dwordx4 v[84:87], v[68:69], off offset:1152
	v_lshl_add_u64 v[68:69], v[108:109], 0, s[24:25]
	global_load_dwordx4 v[80:83], v[68:69], off offset:-256
	global_load_dwordx4 v[76:79], v[68:69], off offset:-128
	global_load_dwordx4 v[72:75], v[68:69], off
	s_nop 0
	global_load_dwordx4 v[68:71], v[68:69], off offset:128
	ds_read_b128 v[164:167], v143
	ds_read_b128 v[168:171], v143 offset:16
	ds_read_b128 v[172:175], v144
	ds_read_b128 v[176:179], v144 offset:16
	s_waitcnt lgkmcnt(2)
	s_and_saveexec_b64 s[6:7], s[4:5]
	v_cvt_pk_bf16_f32 v96, v164, v165
	v_cvt_pk_bf16_f32 v97, v166, v167
	v_and_b32_e32 v98, 0xffff0000, v96
	v_lshlrev_b32_e32 v96, 16, v96
	v_and_b32_e32 v99, 0xffff0000, v97
	v_lshlrev_b32_e32 v97, 16, v97
	v_sub_f32_e32 v164, v164, v96
	v_sub_f32_e32 v165, v165, v98
	v_sub_f32_e32 v166, v166, v97
	v_sub_f32_e32 v167, v167, v99
	v_cvt_pk_bf16_f32 v96, v168, v169
	v_cvt_pk_bf16_f32 v97, v170, v171
	v_and_b32_e32 v98, 0xffff0000, v96
	v_lshlrev_b32_e32 v96, 16, v96
	v_and_b32_e32 v99, 0xffff0000, v97
	v_lshlrev_b32_e32 v97, 16, v97
	v_sub_f32_e32 v168, v168, v96
	v_sub_f32_e32 v169, v169, v98
	v_sub_f32_e32 v170, v170, v97
	v_sub_f32_e32 v171, v171, v99
	s_or_b64 exec, exec, s[6:7]
	v_cvt_pk_bf16_f32 v164, v164, v165
	v_cvt_pk_bf16_f32 v165, v166, v167
	v_cvt_pk_bf16_f32 v166, v168, v169
	v_cvt_pk_bf16_f32 v167, v170, v171
	s_nop 1
	v_mfma_f32_16x16x32_bf16 v[152:155], v[164:167], v[0:3], 0
	ds_read_b128 v[164:167], v145
	ds_read_b128 v[168:171], v145 offset:16
	s_waitcnt lgkmcnt(2)
	s_and_saveexec_b64 s[6:7], s[4:5]
	v_cvt_pk_bf16_f32 v96, v172, v173
	v_cvt_pk_bf16_f32 v97, v174, v175
	v_and_b32_e32 v98, 0xffff0000, v96
	v_lshlrev_b32_e32 v96, 16, v96
	v_and_b32_e32 v99, 0xffff0000, v97
	v_lshlrev_b32_e32 v97, 16, v97
	v_sub_f32_e32 v172, v172, v96
	v_sub_f32_e32 v173, v173, v98
	v_sub_f32_e32 v174, v174, v97
	v_sub_f32_e32 v175, v175, v99
	v_cvt_pk_bf16_f32 v96, v176, v177
	v_cvt_pk_bf16_f32 v97, v178, v179
	v_and_b32_e32 v98, 0xffff0000, v96
	v_lshlrev_b32_e32 v96, 16, v96
	v_and_b32_e32 v99, 0xffff0000, v97
	v_lshlrev_b32_e32 v97, 16, v97
	v_sub_f32_e32 v176, v176, v96
	v_sub_f32_e32 v177, v177, v98
	v_sub_f32_e32 v178, v178, v97
	v_sub_f32_e32 v179, v179, v99
	s_or_b64 exec, exec, s[6:7]
	v_cvt_pk_bf16_f32 v172, v172, v173
	v_cvt_pk_bf16_f32 v173, v174, v175
	v_cvt_pk_bf16_f32 v174, v176, v177
	v_cvt_pk_bf16_f32 v175, v178, v179
	s_nop 1
	v_mfma_f32_16x16x32_bf16 v[156:159], v[172:175], v[0:3], 0
	ds_read_b128 v[172:175], v146
	ds_read_b128 v[176:179], v146 offset:16
	s_waitcnt lgkmcnt(2)
	s_and_saveexec_b64 s[6:7], s[4:5]
	v_cvt_pk_bf16_f32 v96, v164, v165
	v_cvt_pk_bf16_f32 v97, v166, v167
	v_and_b32_e32 v98, 0xffff0000, v96
	v_lshlrev_b32_e32 v96, 16, v96
	v_and_b32_e32 v99, 0xffff0000, v97
	v_lshlrev_b32_e32 v97, 16, v97
	v_sub_f32_e32 v164, v164, v96
	v_sub_f32_e32 v165, v165, v98
	v_sub_f32_e32 v166, v166, v97
	v_sub_f32_e32 v167, v167, v99
	v_cvt_pk_bf16_f32 v96, v168, v169
	v_cvt_pk_bf16_f32 v97, v170, v171
	v_and_b32_e32 v98, 0xffff0000, v96
	v_lshlrev_b32_e32 v96, 16, v96
	v_and_b32_e32 v99, 0xffff0000, v97
	v_lshlrev_b32_e32 v97, 16, v97
	v_sub_f32_e32 v168, v168, v96
	v_sub_f32_e32 v169, v169, v98
	v_sub_f32_e32 v170, v170, v97
	v_sub_f32_e32 v171, v171, v99
	s_or_b64 exec, exec, s[6:7]
	v_cvt_pk_bf16_f32 v164, v164, v165
	v_cvt_pk_bf16_f32 v165, v166, v167
	v_cvt_pk_bf16_f32 v166, v168, v169
	v_cvt_pk_bf16_f32 v167, v170, v171
	s_nop 1
	v_mfma_f32_16x16x32_bf16 v[160:163], v[164:167], v[0:3], 0
	s_waitcnt lgkmcnt(0)
	s_and_saveexec_b64 s[6:7], s[4:5]
	v_cvt_pk_bf16_f32 v96, v172, v173
	v_cvt_pk_bf16_f32 v97, v174, v175
	v_and_b32_e32 v98, 0xffff0000, v96
	v_lshlrev_b32_e32 v96, 16, v96
	v_and_b32_e32 v99, 0xffff0000, v97
	v_lshlrev_b32_e32 v97, 16, v97
	v_sub_f32_e32 v172, v172, v96
	v_sub_f32_e32 v173, v173, v98
	v_sub_f32_e32 v174, v174, v97
	v_sub_f32_e32 v175, v175, v99
	v_cvt_pk_bf16_f32 v96, v176, v177
	v_cvt_pk_bf16_f32 v97, v178, v179
	v_and_b32_e32 v98, 0xffff0000, v96
	v_lshlrev_b32_e32 v96, 16, v96
	v_and_b32_e32 v99, 0xffff0000, v97
	v_lshlrev_b32_e32 v97, 16, v97
	v_sub_f32_e32 v176, v176, v96
	v_sub_f32_e32 v177, v177, v98
	v_sub_f32_e32 v178, v178, v97
	v_sub_f32_e32 v179, v179, v99
	s_or_b64 exec, exec, s[6:7]
	v_cvt_pk_bf16_f32 v172, v172, v173
	v_cvt_pk_bf16_f32 v173, v174, v175
	v_cvt_pk_bf16_f32 v174, v176, v177
	v_cvt_pk_bf16_f32 v175, v178, v179
	s_nop 1
	v_mfma_f32_16x16x32_bf16 v[180:183], v[172:175], v[0:3], 0
	s_nop 3
	v_add_f32_e32 v152, v103, v152
	v_add_f32_e32 v153, v103, v153
	v_add_f32_e32 v154, v103, v154
	v_add_f32_e32 v155, v103, v155
	v_add_f32_e32 v156, v103, v156
	v_add_f32_e32 v157, v103, v157
	v_add_f32_e32 v158, v103, v158
	v_add_f32_e32 v159, v103, v159
	v_add_f32_e32 v160, v103, v160
	v_add_f32_e32 v161, v103, v161
	v_add_f32_e32 v162, v103, v162
	v_add_f32_e32 v163, v103, v163
	v_add_f32_e32 v180, v103, v180
	v_add_f32_e32 v181, v103, v181
	v_add_f32_e32 v182, v103, v182
	v_add_f32_e32 v183, v103, v183
	v_mul_f32_e64 v164, |v152|, s29
	v_mul_f32_e64 v165, |v153|, s29
	v_mul_f32_e64 v166, |v154|, s29
	v_mul_f32_e64 v167, |v155|, s29
	v_mul_f32_e64 v168, |v156|, s29
	v_mul_f32_e64 v169, |v157|, s29
; #define LAS __attribute__((address_space(3)))
; template <bool FULL> ...
;     ...
;                 for (int i = 0; i < 4; ++i) { const float z = z4[i] + bz;
;                     v[i] = (fminf(z, 0.f) - 0.6931471805599453f * __builtin_amdgcn_logf(1.0f + __builtin_amdgcn_exp2f(-1.4426950408889634f * fabsf(z)))) * (1.0f / 16.0f); }
;                 v[1] += v[0]; v[2] += v[1]; v[3] += v[2];
;                 const float tot4 = v[3];
;                 const float p1 = __shfl_up(tot4, 16); float sc = tot4 + (fq >= 1 ? p1 : 0.f);
;                 const float p2 = __shfl_up(sc, 32); sc += (fq >= 2 ? p2 : 0.f);
;                 const float base = carry + (sc - tot4);
; #pragma unroll
;                 for (int i = 0; i < 4; ++i) CUM[(tt * 16 + 4 * fq + i) * 132 + dkc] = v[i] + base;
;                 carry += __shfl(sc, 48 + fr);
;             }
;             if (fq == 0) DEC[dkc] = __builtin_amdgcn_exp2f(1.4426950408889634f * carry);
;             segtot += carry;
;         }
;         __syncthreads();
;         if (c + 1 < GLA_SEGC && tid < 256) *(LAS f32x4*)(ALRS + tid * 4) = *(const f32x4*)(ALR + (tok0 + 64) * 16 + tid * 4);
	v_mul_f32_e64 v170, |v158|, s29
	v_mul_f32_e64 v171, |v159|, s29
	v_mul_f32_e64 v172, |v160|, s29
	v_mul_f32_e64 v173, |v161|, s29
	v_mul_f32_e64 v174, |v162|, s29
	v_mul_f32_e64 v175, |v163|, s29
	v_mul_f32_e64 v176, |v180|, s29
	v_mul_f32_e64 v177, |v181|, s29
	v_mul_f32_e64 v178, |v182|, s29
	v_mul_f32_e64 v179, |v183|, s29
	v_exp_f32_e32 v164, v164
	v_exp_f32_e32 v165, v165
	v_exp_f32_e32 v166, v166
	v_exp_f32_e32 v167, v167
	v_exp_f32_e32 v168, v168
	v_exp_f32_e32 v169, v169
	v_exp_f32_e32 v170, v170
	v_exp_f32_e32 v171, v171
	v_exp_f32_e32 v172, v172
	v_exp_f32_e32 v173, v173
	v_exp_f32_e32 v174, v174
	v_exp_f32_e32 v175, v175
	v_exp_f32_e32 v176, v176
	v_exp_f32_e32 v177, v177
	v_exp_f32_e32 v178, v178
	v_exp_f32_e32 v179, v179
	v_min_f32_e32 v152, 0, v152
	v_min_f32_e32 v153, 0, v153
	v_min_f32_e32 v154, 0, v154
	v_min_f32_e32 v155, 0, v155
	v_min_f32_e32 v156, 0, v156
	v_min_f32_e32 v157, 0, v157
	v_min_f32_e32 v158, 0, v158
	v_min_f32_e32 v159, 0, v159
	v_min_f32_e32 v160, 0, v160
	v_min_f32_e32 v161, 0, v161
	v_min_f32_e32 v162, 0, v162
	v_min_f32_e32 v163, 0, v163
	v_min_f32_e32 v180, 0, v180
	v_min_f32_e32 v181, 0, v181
	v_min_f32_e32 v182, 0, v182
	v_min_f32_e32 v183, 0, v183
	v_add_f32_e32 v164, 1.0, v164
	v_add_f32_e32 v165, 1.0, v165
	v_add_f32_e32 v166, 1.0, v166
	v_add_f32_e32 v167, 1.0, v167
	v_add_f32_e32 v168, 1.0, v168
	v_add_f32_e32 v169, 1.0, v169
	v_add_f32_e32 v170, 1.0, v170
	v_add_f32_e32 v171, 1.0, v171
	v_add_f32_e32 v172, 1.0, v172
	v_add_f32_e32 v173, 1.0, v173
	v_add_f32_e32 v174, 1.0, v174
	v_add_f32_e32 v175, 1.0, v175
	v_add_f32_e32 v176, 1.0, v176
	v_add_f32_e32 v177, 1.0, v177
	v_add_f32_e32 v178, 1.0, v178
	v_add_f32_e32 v179, 1.0, v179
	v_log_f32_e32 v164, v164
	v_log_f32_e32 v165, v165
	v_log_f32_e32 v166, v166
	v_log_f32_e32 v167, v167
	v_log_f32_e32 v168, v168
	v_log_f32_e32 v169, v169
	v_log_f32_e32 v170, v170
	v_log_f32_e32 v171, v171
	v_log_f32_e32 v172, v172
	v_log_f32_e32 v173, v173
	v_log_f32_e32 v174, v174
	v_log_f32_e32 v175, v175
	v_log_f32_e32 v176, v176
	v_log_f32_e32 v177, v177
	v_log_f32_e32 v178, v178
	v_log_f32_e32 v179, v179
	v_fmac_f32_e32 v152, 0xbf317218, v164
	v_fmac_f32_e32 v153, 0xbf317218, v165
	v_fmac_f32_e32 v154, 0xbf317218, v166
	v_fmac_f32_e32 v155, 0xbf317218, v167
	v_fmac_f32_e32 v156, 0xbf317218, v168
	v_fmac_f32_e32 v157, 0xbf317218, v169
	v_fmac_f32_e32 v158, 0xbf317218, v170
	v_fmac_f32_e32 v159, 0xbf317218, v171
	v_fmac_f32_e32 v160, 0xbf317218, v172
	v_fmac_f32_e32 v161, 0xbf317218, v173
	v_fmac_f32_e32 v162, 0xbf317218, v174
	v_fmac_f32_e32 v163, 0xbf317218, v175
	v_fmac_f32_e32 v180, 0xbf317218, v176
	v_fmac_f32_e32 v181, 0xbf317218, v177
	v_fmac_f32_e32 v182, 0xbf317218, v178
	v_fmac_f32_e32 v183, 0xbf317218, v179
	v_mul_f32_e32 v153, 0x3d800000, v153
	v_mul_f32_e32 v157, 0x3d800000, v157
	v_mul_f32_e32 v161, 0x3d800000, v161
	v_mul_f32_e32 v181, 0x3d800000, v181
	v_fmac_f32_e32 v153, 0x3d800000, v152
	v_fmac_f32_e32 v157, 0x3d800000, v156
	v_fmac_f32_e32 v161, 0x3d800000, v160
	v_fmac_f32_e32 v181, 0x3d800000, v180
	v_fmamk_f32 v154, v154, 0x3d800000, v153
	v_fmamk_f32 v158, v158, 0x3d800000, v157
	v_fmamk_f32 v162, v162, 0x3d800000, v161
	v_fmamk_f32 v182, v182, 0x3d800000, v181
	v_fmamk_f32 v155, v155, 0x3d800000, v154
	v_fmamk_f32 v159, v159, 0x3d800000, v158
	v_fmamk_f32 v163, v163, 0x3d800000, v162
	v_fmamk_f32 v183, v183, 0x3d800000, v182
	ds_bpermute_b32 v164, v117, v155
	ds_bpermute_b32 v165, v117, v159
	ds_bpermute_b32 v166, v117, v163
	ds_bpermute_b32 v167, v117, v183
	s_waitcnt lgkmcnt(0)
	v_cndmask_b32_e64 v164, v164, 0, s[0:1]
	v_cndmask_b32_e64 v165, v165, 0, s[0:1]
	v_cndmask_b32_e64 v166, v166, 0, s[0:1]
	v_cndmask_b32_e64 v167, v167, 0, s[0:1]
	v_add_f32_e32 v168, v164, v155
	v_add_f32_e32 v169, v165, v159
	v_add_f32_e32 v170, v166, v163
	v_add_f32_e32 v171, v167, v183
	ds_bpermute_b32 v164, v118, v168
	ds_bpermute_b32 v165, v118, v169
	ds_bpermute_b32 v166, v118, v170
	ds_bpermute_b32 v167, v118, v171
	s_waitcnt lgkmcnt(0)
	v_cndmask_b32_e64 v164, 0, v164, s[4:5]
	v_cndmask_b32_e64 v165, 0, v165, s[4:5]
	v_cndmask_b32_e64 v166, 0, v166, s[4:5]
	v_cndmask_b32_e64 v167, 0, v167, s[4:5]
	v_add_f32_e32 v168, v164, v168
	v_add_f32_e32 v169, v165, v169
	v_add_f32_e32 v170, v166, v170
	v_add_f32_e32 v171, v167, v171
	ds_bpermute_b32 v172, v119, v168
	ds_bpermute_b32 v173, v119, v169
	ds_bpermute_b32 v174, v119, v170
	ds_bpermute_b32 v175, v119, v171
	v_sub_f32_e32 v176, v168, v155
	v_sub_f32_e32 v177, v169, v159
	v_sub_f32_e32 v178, v170, v163
	v_sub_f32_e32 v179, v171, v183
	s_waitcnt lgkmcnt(0)
	v_add_f32_e32 v165, 0, v172
	v_add_f32_e32 v176, 0, v176
	v_add_f32_e32 v166, v165, v173
	v_add_f32_e32 v177, v165, v177
	v_add_f32_e32 v167, v166, v174
	v_add_f32_e32 v178, v166, v178
	v_add_f32_e32 v168, v167, v175
	v_add_f32_e32 v179, v167, v179
	v_fmamk_f32 v152, v152, 0x3d800000, v176
	v_fmamk_f32 v156, v156, 0x3d800000, v177
	v_fmamk_f32 v160, v160, 0x3d800000, v178
	v_fmamk_f32 v180, v180, 0x3d800000, v179
	v_add_f32_e32 v153, v153, v176
	v_add_f32_e32 v157, v157, v177
	v_add_f32_e32 v161, v161, v178
	v_add_f32_e32 v181, v181, v179
	v_add_f32_e32 v154, v154, v176
	v_add_f32_e32 v158, v158, v177
	v_add_f32_e32 v162, v162, v178
	v_add_f32_e32 v182, v182, v179
	v_add_f32_e32 v155, v155, v176
	v_add_f32_e32 v159, v159, v177
	v_add_f32_e32 v163, v163, v178
	v_add_f32_e32 v183, v183, v179
	ds_write_b32 v150, v152
	ds_write_b32 v150, v153 offset:528
	ds_write_b32 v150, v154 offset:1056
	ds_write_b32 v150, v155 offset:1584
	ds_write_b32 v150, v156 offset:8448
	ds_write_b32 v150, v157 offset:8976
	ds_write_b32 v150, v158 offset:9504
	ds_write_b32 v150, v159 offset:10032
	ds_write_b32 v150, v160 offset:16896
	ds_write_b32 v150, v161 offset:17424
	ds_write_b32 v150, v162 offset:17952
	ds_write_b32 v150, v163 offset:18480
	ds_write_b32 v150, v180 offset:25344
	ds_write_b32 v150, v181 offset:25872
	ds_write_b32 v150, v182 offset:26400
	ds_write_b32 v150, v183 offset:26928
	v_mov_b32_e32 v92, v168
	s_and_saveexec_b64 s[6:7], s[0:1]
	v_mul_f32_e32 v168, 0x3fb8aa3b, v168
	v_exp_f32_e32 v168, v168
	s_nop 0
	ds_write_b32 v120, v168
.LBB0_311:
	s_or_b64 exec, exec, s[6:7]
	s_cmp_lg_u32 s24, 0xe0000
	s_cselect_b64 s[6:7], -1, 0
	s_and_b64 s[72:73], vcc, s[6:7]
	s_waitcnt lgkmcnt(0)
	s_barrier
	s_and_saveexec_b64 s[6:7], s[72:73]
	s_cbranch_execz .LBB0_300
	s_waitcnt vmcnt(6)
	ds_write_b128 v100, v[200:203]
	s_branch .LBB0_300

; __device__ __forceinline__ unsigned xb_ld(unsigned* p)              { return __hip_atomic_load(p, __ATOMIC_RELAXED, __HIP_MEMORY_SCOPE_AGENT); }
; __device__ __forceinline__ unsigned xb_add(unsigned* p, unsigned v) { return __hip_atomic_fetch_add(p, v, __ATOMIC_RELAXED, __HIP_MEMORY_SCOPE_AGENT); }
; #define XB_SPIN(cond, bar) do { unsigned _sp = 0; while (cond) { __builtin_amdgcn_s_sleep(1); \
;     if ((++_sp & 255u) == 0u) { if (xb_ld(&(bar)[XB_TMO])) break; if (_sp > XB_SPIN_CAP) { atomicAdd(&(bar)[XB_TMO], 1u); break; } } } } while (0)
; __device__ __forceinline__ void xcd_barrier(const XcdBarrier& b) {
;     asm volatile("s_waitcnt vmcnt(0)" ::: "memory");
;     __syncthreads();
;     if (threadIdx.x == 0) {
;         unsigned* bar = b.bar;
;         __builtin_amdgcn_s_waitcnt(0);
;         unsigned nloc = b.st[0], nx = b.st[1];
;         if (nloc == 0u) { xcd_barrier_complete(bar, b.x, nloc, nx); b.st[0] = nloc; b.st[1] = nx; }
;         const unsigned old = xb_add(&bar[XB_XSUB(b.x)], 1u);
;         const unsigned gen = old / nloc;
;         if (old + 1u == (gen + 1u) * nloc) {
;             __builtin_amdgcn_fence(__ATOMIC_RELEASE, "agent");
;             asm volatile("s_waitcnt vmcnt(0)" ::: "memory");
;             const unsigned og = xb_add(&bar[XB_TOP], 1u);
;             const unsigned tg = og / nx;
;             if (og + 1u == (tg + 1u) * nx) xb_add(&bar[XB_TOPGEN], 1u);
;             else XB_SPIN(xb_ld(&bar[XB_TOPGEN]) == tg, bar);
;             __builtin_amdgcn_fence(__ATOMIC_ACQUIRE, "agent");
;             xb_add(&bar[XB_XGEN(b.x)], 1u);
;             asm volatile("s_waitcnt vmcnt(0)" ::: "memory");
;         } else {
;             XB_SPIN(xb_ld(&bar[XB_XGEN(b.x)]) == gen, bar);
;             __builtin_amdgcn_fence(__ATOMIC_ACQUIRE, "agent");
;             asm volatile("s_waitcnt vmcnt(0)" ::: "memory");
;         }
.LBB0_392:
	s_or_b64 exec, exec, s[8:9]
	v_cvt_f32_u32_e32 v4, v2
	s_waitcnt vmcnt(0)
	v_readfirstlane_b32 s3, v3
	v_sub_u32_e32 v3, 0, v2
	v_rcp_iflag_f32_e32 v4, v4
	v_add_u32_e32 v5, s3, v1
	v_mul_f32_e32 v4, 0x4f7ffffe, v4
	v_cvt_u32_f32_e32 v4, v4
	v_mul_lo_u32 v1, v3, v4
	v_mul_hi_u32 v1, v4, v1
	v_add_u32_e32 v1, v4, v1
	v_mul_hi_u32 v1, v5, v1
	v_mul_lo_u32 v3, v1, v2
	v_sub_u32_e32 v3, v5, v3
	v_add_u32_e32 v4, 1, v1
	v_cmp_ge_u32_e32 vcc, v3, v2
	s_nop 1
	v_cndmask_b32_e32 v1, v1, v4, vcc
	v_sub_u32_e32 v4, v3, v2
	v_cndmask_b32_e32 v3, v3, v4, vcc
	v_add_u32_e32 v4, 1, v1
	v_cmp_ge_u32_e32 vcc, v3, v2
	v_add_u32_e32 v3, 1, v5
	s_nop 0
	v_cndmask_b32_e32 v1, v1, v4, vcc
	v_mul_lo_u32 v4, v2, v1
	v_add_u32_e32 v2, v4, v2
	v_cmp_ne_u32_e32 vcc, v3, v2
	s_and_saveexec_b64 s[6:7], vcc
	s_xor_b64 s[6:7], exec, s[6:7]
	s_cbranch_execz .LBB0_406
	v_cmp_eq_u32_e32 vcc, v5, v4
	s_cbranch_vccz .Lfl_p2a
	buffer_wbl2 sc1
.Lfl_p2a:
	s_waitcnt lgkmcnt(0)
	v_mov_b32_e32 v0, 0x2000
	global_load_dword v0, v0, s[4:5] offset:1024 sc1
	s_add_u32 s12, s4, 0x2400
	s_addc_u32 s13, s5, 0
	s_waitcnt vmcnt(0)
	v_cmp_eq_u32_e32 vcc, v0, v1
	s_and_saveexec_b64 s[8:9], vcc
	s_cbranch_execz .LBB0_405
	s_add_u32 s10, s68, 0x100200
	s_addc_u32 s11, s69, 0
	s_mov_b32 s3, 1
	s_mov_b64 s[14:15], 0
	v_mov_b32_e32 v0, 0
	s_branch .LBB0_396
